# barrier relocation + static s_setprio 1 for waves 4-7 inside all four mixer unit types
# speedup vs baseline: 1.0068x; 1.0068x over previous
; #define QLOOP2(qi_, r2_, n_, ...) for (;;) { if (tid == 0) s_item = (int)atomicAdd(ctr + 64 * (qi_) + 32 * (r2_), 1u); __syncthreads(); const int item = s_item; __syncthreads(); if (item >= (n_)) break; __VA_ARGS__ }
; template <int PHM, int MIXM>
; __global__ void __launch_bounds__(512, 2) mega(Args Aval) {
;     ...
;             for (int r2 = 0; r2 < ((PROBE_DUP & 16) ? 2 : 1); ++r2) if (MIXM & 1) QLOOP2(0, r2, 256, { const int L = 15 - (item >> 4), r = item & 15; flash_unit<0>(A, l, r >> 2, r & 3, L, lds); })
;             for (int r2 = 0; r2 < ((PROBE_DUP & 32) ? 2 : 1); ++r2) if (MIXM & 2) QLOOP2(1, r2, 256, { const int L = 15 - (item >> 4), r = item & 15; flash_unit<2>(A, l, r >> 2, r & 3, L, lds); })
;             for (int r2 = 0; r2 < ((PROBE_DUP & 64) ? 2 : 1); ++r2) if (MIXM & 8) QLOOP2(2, r2, 256, { s5_unit(A, l, item, lds, wave, lane); })
.LBB0_784:
	s_lshl_b32 s8, s92, 9
	s_lshl_b32 s9, s92, 5
	s_branch .LBB0_786
.LBB0_785:
	s_setprio 0
	s_and_b64 vcc, exec, s[2:3]
	s_cbranch_vccnz .LBB0_794
.LBB0_786:
	s_and_saveexec_b64 s[2:3], s[30:31]
	s_cbranch_execz .LBB0_790
	s_mov_b64 s[6:7], exec
	v_mbcnt_lo_u32_b32 v0, s6, 0
	v_mbcnt_hi_u32_b32 v0, s7, v0
	v_cmp_eq_u32_e32 vcc, 0, v0
	s_and_saveexec_b64 s[4:5], vcc
	s_cbranch_execz .LBB0_789
	s_bcnt1_i32_b64 s6, s[6:7]
	v_mov_b32_e32 v1, s6
	v_readlane_b32 s6, v255, 25
	v_readlane_b32 s7, v255, 26
	s_nop 4
	global_atomic_add v1, v177, v1, s[6:7] offset:512 sc0

; __device__ __forceinline__ void s5_unit(ArgsP A, int l, int unit, unsigned char* lds, int wave_, int lane_) {
;     int tid_ = threadIdx.x; asm volatile("" : "+v"(tid_)); const int lane = tid_ & 63, wave = __builtin_amdgcn_readfirstlane(tid_ >> 6);
;     const int b = unit >> 6, c = unit & 63, rowbase = b * SEQ + 64 * c;
;     const bf16_t* PROJ = (const bf16_t*)(A->ws + WS_PROJ);
;     bf16_t* ys = (bf16_t*)lds;
;     float* Hs = (float*)(lds + 66560 + wave * 8448);
;     const f32x2_t* E = (const f32x2_t*)(A->ws + WS_S5E);
;     for (int gi = 0; gi < 4; ++gi) {
;         const int g = 4 * wave + gi;
;         S5Coef C; bf16x8 bm[8]; s5_fetch(A, l, g, lane, C, bm);
;         bf16x8 chl[8];
;         { const bf16x8* ct = (const bf16x8*)(A->ws + WS_S5T + (size_t)(l * 32 + g) * S5T_BYTES + 9216);
; #pragma unroll
;           for (int q = 0; q < 8; ++q) chl[q] = ct[q * 64 + lane]; }
;         const f32x2_t hin = ((const f32x2_t*)(A->ws + WS_S5H))[(size_t)((b * 64 + c) * 32 + g) * 64 + lane]; float hr = hin.x, hi = hin.y;
;         u32x4 uw[4];
; #pragma unroll
;         for (int blk = 0; blk < 4; ++blk) uw[blk] = s5_load_ua(PROJ, rowbase + 16 * blk, g, lane);
;         const float dv = A->in[20][l * 512 + 16 * g + (lane & 15)];
.LBB0_790:
	s_or_b64 exec, exec, s[2:3]
	s_waitcnt lgkmcnt(0)
	s_barrier
	ds_read_b32 v0, v177 offset:8
	s_mov_b64 s[2:3], -1
	s_waitcnt lgkmcnt(0)
	s_barrier
	v_cmp_gt_i32_e32 vcc, s68, v0
	v_readfirstlane_b32 s4, v0
	s_cbranch_vccz .LBB0_785
	v_readfirstlane_b32 s100, v238
	s_cmp_lt_u32 s100, 0x100
	s_cbranch_scc1 .Lprio_skip_s5
	s_setprio 1
.Lprio_skip_s5:
	v_mov_b32_e32 v2, v238
	s_lshl_b32 s10, s4, 6
	v_readfirstlane_b32 s5, v2
	s_ashr_i32 s6, s5, 6
	v_lshrrev_b32_e32 v0, 2, v2
	s_mul_i32 s2, s6, 0x2100
	v_and_b32_e32 v3, 12, v0
	v_bfe_u32 v0, v2, 2, 4
	s_add_i32 s2, s2, 16
	v_and_b32_e32 v1, 12, v0
	v_or_b32_e32 v0, 3, v0
	s_add_i32 s7, s2, 0x10400
	v_and_b32_e32 v104, 15, v2
	v_mul_u32_u24_e32 v1, 0x84, v1
	v_mul_u32_u24_e32 v0, 0x84, v0
	v_and_b32_e32 v105, 63, v2
	v_lshl_add_u32 v4, v104, 2, s7
	v_lshlrev_b32_e32 v1, 2, v1
	v_lshlrev_b32_e32 v0, 2, v0
	v_add_u32_e32 v106, v4, v1
	v_add_u32_e32 v107, v4, v0
	v_lshlrev_b32_e32 v4, 2, v105
	v_or_b32_e32 v5, 0xc0, v4
	v_add_u32_e32 v5, s7, v5
	v_add_u32_e32 v108, v5, v1
	v_add_u32_e32 v109, v5, v0
	v_or_b32_e32 v5, 0x1c0, v4
	v_add_u32_e32 v5, s7, v5
	v_add_u32_e32 v110, v5, v1
	v_lshlrev_b32_e32 v1, 1, v2
	s_lshl_b32 s15, s4, 5
	v_add_u32_e32 v111, v5, v0
	v_mul_u32_u24_e32 v0, 0x210, v104
	v_and_b32_e32 v1, 0x60, v1
	s_lshl_b32 s4, s6, 7
	v_add3_u32 v113, s7, v0, v1
	v_mov_b32_e32 v0, s4
	s_movk_i32 s4, 0x410
	v_mad_u32_u24 v0, v3, s4, v0
	s_and_b32 s4, s5, 0xffffffc0
	v_add_u32_e32 v112, s7, v4
	v_lshlrev_b32_e32 v4, 1, v104
	s_ashr_i32 s5, s4, 31
	s_lshl_b32 s14, s6, 2
	v_or_b32_e32 v0, v0, v4
	s_or_b32 s16, s10, 48
	s_lshl_b64 s[6:7], s[4:5], 1
	v_add_u32_e32 v114, 16, v0
	v_or_b32_e32 v5, s16, v3
	v_mov_b64_e32 v[0:1], s[6:7]
	s_or_b32 s5, s10, 32
	v_mad_i64_i32 v[80:81], s[12:13], v5, s35, v[0:1]
	v_or_b32_e32 v5, s5, v3
	s_or_b32 s17, s10, 16
	v_mad_i64_i32 v[82:83], s[12:13], v5, s35, v[0:1]
	v_or_b32_e32 v5, s17, v3
	v_or_b32_e32 v3, s10, v3
	v_mad_i64_i32 v[84:85], s[12:13], v5, s35, v[0:1]
	v_mad_i64_i32 v[86:87], s[12:13], v3, s35, v[0:1]
	v_or_b32_e32 v0, s16, v104
	v_mad_i64_i32 v[0:1], s[12:13], v0, s35, 0
	v_and_b32_e32 v2, 16, v2
	v_or_b32_e32 v0, v0, v2
	v_lshl_add_u64 v[0:1], v[0:1], 0, s[6:7]
	s_mov_b64 s[20:21], 0x18f90000
	v_lshl_add_u64 v[88:89], v[0:1], 0, s[20:21]
	v_or_b32_e32 v0, s5, v104
	v_mad_i64_i32 v[0:1], s[12:13], v0, s35, 0
	v_or_b32_e32 v0, v0, v2
	v_lshl_add_u64 v[0:1], v[0:1], 0, s[6:7]
	v_lshl_add_u64 v[90:91], v[0:1], 0, s[20:21]
	v_or_b32_e32 v0, s17, v104
	v_mad_i64_i32 v[0:1], s[12:13], v0, s35, 0
	v_or_b32_e32 v0, v0, v2
	v_lshl_add_u64 v[0:1], v[0:1], 0, s[6:7]
	v_lshl_add_u64 v[92:93], v[0:1], 0, s[20:21]
	v_or_b32_e32 v0, s10, v104
	v_mad_i64_i32 v[0:1], s[12:13], v0, s35, 0
	v_or_b32_e32 v0, v0, v2
	v_lshl_add_u64 v[0:1], v[0:1], 0, s[6:7]
	s_add_i32 s6, s15, s14
	s_ashr_i32 s7, s6, 31
	s_load_dwordx2 s[2:3], s[26:27], 0x148
	s_add_i32 s11, s8, s4
	s_lshl_b64 s[6:7], s[6:7], 9
	s_add_u32 s5, s6, 0x2e8c0000
	s_addc_u32 s6, s7, 0
	v_lshl_or_b32 v96, v105, 3, s5
	s_add_i32 s5, s9, s14
	v_mov_b32_e32 v97, s6
	s_mul_hi_i32 s6, s5, 0x4400
	s_mulk_i32 s5, 0x4400
	v_add_u32_e32 v78, s11, v104
	v_or_b32_e32 v80, v80, v4
	v_or_b32_e32 v82, v82, v4
	v_or_b32_e32 v84, v84, v4
	v_or_b32_e32 v86, v86, v4
	v_lshl_add_u64 v[94:95], v[0:1], 0, s[20:21]
	v_lshl_or_b32 v98, v105, 4, s5
	v_mov_b32_e32 v99, s6
	s_mov_b32 s5, 0
	s_mov_b32 s12, 0x18f90000
	s_mov_b32 s13, 0x18f92000
	s_mov_b64 s[14:15], 0x200
